# adds: same fully-masked tile skip for the last two key tiles of every FoX attention unit
# speedup vs baseline: 1.0120x; 1.0061x over previous
.LBB0_373:
	s_sub_i32 s1, s29, 0x5f
	s_cmp_ge_i32 s1, s28
	s_cbranch_scc0 .Lfox_L2_full
	v_add_f32_e32 v82, v119, v120
	v_add_f32_e32 v111, v111, v82
	s_waitcnt vmcnt(0)
	s_addk_i32 s29, 0x80
	s_add_i32 s0, s16, 2
	s_add_i32 s1, s16, 1
	v_add_u32_e32 v113, 0x200, v113
	v_add_u32_e32 v114, 0xffffff80, v114
	s_cmp_lt_i32 s1, s5
	s_barrier
	s_cbranch_scc0 .LBB0_382
	s_mov_b32 s16, s0
	s_branch .LBB0_364

.LBB0_382:
	s_cmp_ge_i32 s16, s5
	s_cbranch_scc1 .LBB0_390
	s_lshl_b32 s1, s16, 6
	s_add_i32 s1, s1, s4
	s_sub_i32 s1, s1, 32
	s_cmp_ge_i32 s1, s28
	s_cbranch_scc0 .Lfox_T_full
	s_waitcnt vmcnt(0)
	s_barrier
	s_branch .LBB0_390
.Lfox_T_full:
	s_lshl_b32 s0, s16, 6
	v_xad_u32 v72, v100, v138, v19
	ds_read_b128 v[68:71], v72 offset:40960
	s_waitcnt lgkmcnt(0)
	v_mfma_f32_32x32x16_bf16 v[52:67], v[68:71], v[96:99], v[36:51]
	ds_read_b128 v[68:71], v72 offset:45056
	s_waitcnt lgkmcnt(0)
	v_mfma_f32_32x32x16_bf16 v[36:51], v[68:71], v[96:99], v[36:51]
	v_or_b32_e32 v68, 32, v100
	v_xad_u32 v72, v68, v138, v19
	ds_read_b128 v[68:71], v72 offset:40960
	s_waitcnt lgkmcnt(0)
	v_mfma_f32_32x32x16_bf16 v[52:67], v[68:71], v[92:95], v[52:67]
	ds_read_b128 v[68:71], v72 offset:45056
	s_waitcnt lgkmcnt(0)
	v_mfma_f32_32x32x16_bf16 v[36:51], v[68:71], v[92:95], v[36:51]
	v_or_b32_e32 v68, 64, v100
	v_xad_u32 v72, v68, v138, v19
	ds_read_b128 v[68:71], v72 offset:40960
	s_waitcnt lgkmcnt(0)
	v_mfma_f32_32x32x16_bf16 v[52:67], v[68:71], v[88:91], v[52:67]
	ds_read_b128 v[68:71], v72 offset:45056
	s_waitcnt lgkmcnt(0)
	v_mfma_f32_32x32x16_bf16 v[36:51], v[68:71], v[88:91], v[36:51]
	v_or_b32_e32 v68, 0x60, v100
	v_xad_u32 v19, v68, v138, v19
	ds_read_b128 v[68:71], v19 offset:40960
	s_waitcnt lgkmcnt(0)
	v_mfma_f32_32x32x16_bf16 v[52:67], v[68:71], v[84:87], v[52:67]
	ds_read_b128 v[68:71], v19 offset:45056
	s_waitcnt lgkmcnt(0)
	v_mfma_f32_32x32x16_bf16 v[36:51], v[68:71], v[84:87], v[36:51]
	s_lshl_b32 s1, s16, 8
	s_add_i32 s1, s1, 0
	v_lshl_add_u32 v19, v132, 2, s1
	ds_read_b128 v[70:73], v19 offset:51200
	ds_read_b128 v[74:77], v19 offset:51328
	ds_read_b128 v[78:81], v19 offset:51232
	ds_read_b128 v[82:85], v19 offset:51360
	s_add_i32 s0, s0, s4
	s_or_b32 s1, s0, 63
	s_waitcnt lgkmcnt(2)
	v_sub_f32_e32 v68, v36, v74
	v_sub_f32_e32 v69, v37, v75
	v_sub_f32_e32 v54, v54, v72
	v_sub_f32_e32 v55, v55, v73
	s_waitcnt lgkmcnt(1)
	v_sub_f32_e32 v56, v56, v78
	s_waitcnt lgkmcnt(0)
	v_sub_f32_e32 v72, v40, v82
	v_sub_f32_e32 v57, v57, v79
	v_sub_f32_e32 v73, v41, v83
	v_sub_f32_e32 v58, v58, v80
	v_sub_f32_e32 v74, v42, v84
	v_sub_f32_e32 v59, v59, v81
	ds_read_b128 v[78:81], v19 offset:51392
	v_sub_f32_e32 v75, v43, v85
	ds_read_b128 v[82:85], v19 offset:51424
	s_cmp_le_i32 s1, s28
	v_sub_f32_e32 v70, v52, v70
	v_sub_f32_e32 v71, v53, v71
	v_sub_f32_e32 v52, v38, v76
	v_sub_f32_e32 v53, v39, v77
	ds_read_b128 v[36:39], v19 offset:51264
	ds_read_b128 v[40:43], v19 offset:51296
	s_waitcnt lgkmcnt(1)
	v_sub_f32_e32 v60, v60, v36
	v_sub_f32_e32 v76, v44, v78
	v_sub_f32_e32 v61, v61, v37
	v_sub_f32_e32 v77, v45, v79
	v_sub_f32_e32 v78, v62, v38
	v_sub_f32_e32 v62, v46, v80
	v_sub_f32_e32 v79, v63, v39
	v_sub_f32_e32 v63, v47, v81
	s_waitcnt lgkmcnt(0)
	v_sub_f32_e32 v64, v64, v40
	v_sub_f32_e32 v80, v48, v82
	v_sub_f32_e32 v65, v65, v41
	v_sub_f32_e32 v81, v49, v83
	v_sub_f32_e32 v66, v66, v42
	v_sub_f32_e32 v82, v50, v84
	v_sub_f32_e32 v67, v67, v43
	v_sub_f32_e32 v83, v51, v85
	s_cbranch_scc1 .LBB0_385
	v_subrev_u32_e32 v19, s0, v137
	v_cmp_lt_i32_e32 vcc, -1, v19
	s_or_b32 s1, s0, 2
	s_nop 0
	v_cndmask_b32_e32 v70, v130, v70, vcc
	v_cmp_lt_i32_e32 vcc, 31, v19
	v_xad_u32 v19, s0, -1, v137
	s_nop 0
	v_cndmask_b32_e32 v68, v130, v68, vcc
	v_cmp_lt_i32_e32 vcc, -1, v19
	s_nop 1
	v_cndmask_b32_e32 v71, v130, v71, vcc
	v_cmp_lt_i32_e32 vcc, 31, v19
	v_subrev_u32_e32 v19, s1, v137
	s_or_b32 s1, s0, 3
	v_cndmask_b32_e32 v69, v130, v69, vcc
	v_cmp_lt_i32_e32 vcc, -1, v19
	s_nop 1
	v_cndmask_b32_e32 v54, v130, v54, vcc
	v_cmp_lt_i32_e32 vcc, 31, v19
	v_subrev_u32_e32 v19, s1, v137
	s_or_b32 s1, s0, 8
	v_cndmask_b32_e32 v52, v130, v52, vcc
	v_cmp_lt_i32_e32 vcc, -1, v19
	s_nop 1
	v_cndmask_b32_e32 v55, v130, v55, vcc
	v_cmp_lt_i32_e32 vcc, 31, v19
	v_subrev_u32_e32 v19, s1, v137
	s_or_b32 s1, s0, 9
	v_cndmask_b32_e32 v53, v130, v53, vcc
	v_cmp_lt_i32_e32 vcc, -1, v19
	s_nop 1
	v_cndmask_b32_e32 v56, v130, v56, vcc
	v_cmp_lt_i32_e32 vcc, 31, v19
	v_subrev_u32_e32 v19, s1, v137
	s_or_b32 s1, s0, 10
	v_cndmask_b32_e32 v72, v130, v72, vcc
	v_cmp_lt_i32_e32 vcc, -1, v19
	s_nop 1
	v_cndmask_b32_e32 v57, v130, v57, vcc
	v_cmp_lt_i32_e32 vcc, 31, v19
	v_subrev_u32_e32 v19, s1, v137
	s_or_b32 s1, s0, 11
	v_cndmask_b32_e32 v73, v130, v73, vcc
	v_cmp_lt_i32_e32 vcc, -1, v19
	s_nop 1
	v_cndmask_b32_e32 v58, v130, v58, vcc
	v_cmp_lt_i32_e32 vcc, 31, v19
	v_subrev_u32_e32 v19, s1, v137
	s_or_b32 s1, s0, 16
	v_cndmask_b32_e32 v74, v130, v74, vcc
	v_cmp_lt_i32_e32 vcc, -1, v19
	s_nop 1
	v_cndmask_b32_e32 v59, v130, v59, vcc
	v_cmp_lt_i32_e32 vcc, 31, v19
	v_subrev_u32_e32 v19, s1, v137
	s_or_b32 s1, s0, 17
	v_cndmask_b32_e32 v75, v130, v75, vcc
	v_cmp_lt_i32_e32 vcc, -1, v19
	s_nop 1
	v_cndmask_b32_e32 v60, v130, v60, vcc
	v_cmp_lt_i32_e32 vcc, 31, v19
	v_subrev_u32_e32 v19, s1, v137
	s_or_b32 s1, s0, 18
	v_cndmask_b32_e32 v76, v130, v76, vcc
	v_cmp_lt_i32_e32 vcc, -1, v19
	s_nop 1
	v_cndmask_b32_e32 v61, v130, v61, vcc
	v_cmp_lt_i32_e32 vcc, 31, v19
	v_subrev_u32_e32 v19, s1, v137
	s_or_b32 s1, s0, 19
	v_cndmask_b32_e32 v77, v130, v77, vcc
	v_cmp_lt_i32_e32 vcc, -1, v19
	s_nop 1
	v_cndmask_b32_e32 v78, v130, v78, vcc
	v_cmp_lt_i32_e32 vcc, 31, v19
	v_subrev_u32_e32 v19, s1, v137
	s_or_b32 s1, s0, 24
	v_cndmask_b32_e32 v62, v130, v62, vcc
	v_cmp_lt_i32_e32 vcc, -1, v19
	s_nop 1
	v_cndmask_b32_e32 v79, v130, v79, vcc
	v_cmp_lt_i32_e32 vcc, 31, v19
	v_subrev_u32_e32 v19, s1, v137
	s_or_b32 s1, s0, 25
	v_cndmask_b32_e32 v63, v130, v63, vcc
	v_cmp_lt_i32_e32 vcc, -1, v19
	s_nop 1
	v_cndmask_b32_e32 v64, v130, v64, vcc
	v_cmp_lt_i32_e32 vcc, 31, v19
	v_subrev_u32_e32 v19, s1, v137
	s_or_b32 s1, s0, 26
	v_cndmask_b32_e32 v80, v130, v80, vcc
	v_cmp_lt_i32_e32 vcc, -1, v19
	s_or_b32 s0, s0, 27
	s_nop 0
	v_cndmask_b32_e32 v65, v130, v65, vcc
	v_cmp_lt_i32_e32 vcc, 31, v19
	v_subrev_u32_e32 v19, s1, v137
	s_nop 0
	v_cndmask_b32_e32 v81, v130, v81, vcc
	v_cmp_lt_i32_e32 vcc, -1, v19
	s_nop 1
	v_cndmask_b32_e32 v66, v130, v66, vcc
	v_cmp_lt_i32_e32 vcc, 31, v19
	v_subrev_u32_e32 v19, s0, v137
	s_nop 0
	v_cndmask_b32_e32 v82, v130, v82, vcc
	v_cmp_lt_i32_e32 vcc, -1, v19
	s_nop 1
	v_cndmask_b32_e32 v67, v130, v67, vcc
	v_cmp_lt_i32_e32 vcc, 31, v19
	s_nop 1
	v_cndmask_b32_e32 v83, v130, v83, vcc
